# barrier: the per-workgroup L1 invalidate is issued with the arrival (no loads happen until release), so the release-to-go path has no acquire wait
# speedup vs baseline: 1.0068x; 1.0011x over previous
; DI void grid_barrier(unsigned* bar, unsigned gen) {
;   asm volatile("s_waitcnt vmcnt(0)" ::: "memory");
;   __syncthreads();
;   if (threadIdx.x == 0) {
;     __builtin_amdgcn_fence(__ATOMIC_RELEASE, "agent");
;     const unsigned grp = blockIdx.x & 15u;
;     const unsigned nblk = (gridDim.x + 15u - grp) >> 4;
;     unsigned old = __hip_atomic_fetch_add(bar + 64 * (1 + grp), 1u, __ATOMIC_RELAXED, __HIP_MEMORY_SCOPE_AGENT);
;     if (old + 1u == nblk * gen) {
;       unsigned g = __hip_atomic_fetch_add(bar, 1u, __ATOMIC_RELAXED, __HIP_MEMORY_SCOPE_AGENT);
;       if (g + 1u == 16u * gen) {
;         for (int i = 0; i < 16; ++i) __hip_atomic_store(bar + 64 * (17 + i), gen, __ATOMIC_RELAXED, __HIP_MEMORY_SCOPE_AGENT);
;       }
;     }
;     while (__hip_atomic_load(bar + 64 * (17 + grp), __ATOMIC_RELAXED, __HIP_MEMORY_SCOPE_AGENT) < gen) __builtin_amdgcn_s_sleep(4);
;     __builtin_amdgcn_fence(__ATOMIC_ACQUIRE, "agent");
;   }
;   __syncthreads();
; }
.Lmy_xb_glob:
	v_mov_b32_e32 v0, s17
	v_add_u32_e32 v0, 0x1400, v0
	global_atomic_add v3, v0, v2, s[12:13] sc0
	buffer_inv sc1
	s_waitcnt vmcnt(0)
	v_readfirstlane_b32 s18, v3
	s_add_i32 s18, s18, 1
	s_mul_i32 s19, s20, s15
	s_cmp_eq_u32 s18, s19
	s_cbranch_scc0 .Lmy_xb_follow
	buffer_wbl2 sc1
	s_waitcnt vmcnt(0)
	v_mov_b32_e32 v0, 0x3400
	global_atomic_add v3, v0, v2, s[12:13] sc0
	s_waitcnt vmcnt(0)
	v_readfirstlane_b32 s18, v3
	s_add_i32 s18, s18, 1
	s_mul_i32 s19, s20, s16
	v_mov_b32_e32 v0, 0x3500
	s_cmp_eq_u32 s18, s19
	s_cbranch_scc0 .Lmy_xb_spin_top
	global_atomic_add v0, v2, s[12:13]
	s_branch .Lmy_xb_lead_acq

; DI void grid_barrier(unsigned* bar, unsigned gen) {
;   asm volatile("s_waitcnt vmcnt(0)" ::: "memory");
;   __syncthreads();
;   if (threadIdx.x == 0) {
;     __builtin_amdgcn_fence(__ATOMIC_RELEASE, "agent");
;     const unsigned grp = blockIdx.x & 15u;
;     const unsigned nblk = (gridDim.x + 15u - grp) >> 4;
;     unsigned old = __hip_atomic_fetch_add(bar + 64 * (1 + grp), 1u, __ATOMIC_RELAXED, __HIP_MEMORY_SCOPE_AGENT);
;     if (old + 1u == nblk * gen) {
;       unsigned g = __hip_atomic_fetch_add(bar, 1u, __ATOMIC_RELAXED, __HIP_MEMORY_SCOPE_AGENT);
;       if (g + 1u == 16u * gen) {
;         for (int i = 0; i < 16; ++i) __hip_atomic_store(bar + 64 * (17 + i), gen, __ATOMIC_RELAXED, __HIP_MEMORY_SCOPE_AGENT);
;       }
;     }
;     while (__hip_atomic_load(bar + 64 * (17 + grp), __ATOMIC_RELAXED, __HIP_MEMORY_SCOPE_AGENT) < gen) __builtin_amdgcn_s_sleep(4);
;     __builtin_amdgcn_fence(__ATOMIC_ACQUIRE, "agent");
;   }
;   __syncthreads();
; }
.Lmy_xb_lead_acq:
	v_mov_b32_e32 v0, s17
	v_add_u32_e32 v0, 0x2400, v0
	global_atomic_add v0, v2, s[12:13]
	s_branch .LBB0_28

; DI void grid_barrier(unsigned* bar, unsigned gen) {
;   asm volatile("s_waitcnt vmcnt(0)" ::: "memory");
;   __syncthreads();
;   if (threadIdx.x == 0) {
;     __builtin_amdgcn_fence(__ATOMIC_RELEASE, "agent");
;     const unsigned grp = blockIdx.x & 15u;
;     const unsigned nblk = (gridDim.x + 15u - grp) >> 4;
;     unsigned old = __hip_atomic_fetch_add(bar + 64 * (1 + grp), 1u, __ATOMIC_RELAXED, __HIP_MEMORY_SCOPE_AGENT);
;     if (old + 1u == nblk * gen) {
;       unsigned g = __hip_atomic_fetch_add(bar, 1u, __ATOMIC_RELAXED, __HIP_MEMORY_SCOPE_AGENT);
;       if (g + 1u == 16u * gen) {
;         for (int i = 0; i < 16; ++i) __hip_atomic_store(bar + 64 * (17 + i), gen, __ATOMIC_RELAXED, __HIP_MEMORY_SCOPE_AGENT);
;       }
;     }
;     while (__hip_atomic_load(bar + 64 * (17 + grp), __ATOMIC_RELAXED, __HIP_MEMORY_SCOPE_AGENT) < gen) __builtin_amdgcn_s_sleep(4);
;     __builtin_amdgcn_fence(__ATOMIC_ACQUIRE, "agent");
;   }
;   __syncthreads();
; }
.Lmy_xb_spin_loc:
	s_sleep 1
	global_load_dword v3, v0, s[12:13] sc1
	s_waitcnt vmcnt(0)
	v_readfirstlane_b32 s18, v3
	s_cmp_lt_u32 s18, s20
	s_cbranch_scc1 .Lmy_xb_spin_loc
	s_branch .LBB0_28
.Lmy_xb_local:
	v_mov_b32_e32 v0, s17
	v_add_u32_e32 v0, 0x1480, v0
	global_atomic_add v3, v0, v2, s[12:13] sc0
	buffer_inv sc1
	v_mov_b32_e32 v4, s17
	v_add_u32_e32 v4, 0x2480, v4
	s_mul_i32 s21, s19, s15
	s_waitcnt vmcnt(0)
	v_readfirstlane_b32 s18, v3
	s_add_i32 s18, s18, 1
	s_cmp_eq_u32 s18, s21
	s_cbranch_scc0 .Lmy_xb_lspin
	global_atomic_add v4, v2, s[12:13]
	s_branch .Lmy_xb_lacq
